# non-temporal stores for the q up-projection output (read once per attention unit) to keep K/V in the memory-side cache
# baseline (speedup 1.0000x reference)
.LBB0_1269:
	v_lshl_or_b32 v146, s64, 8, v150
	v_lshl_add_u32 v156, s63, 8, v148
	v_ashrrev_i32_e32 v147, 31, v146
	v_mov_b64_e32 v[144:145], s[58:59]
	v_mad_i64_i32 v[154:155], s[16:17], v156, s62, v[144:145]
	v_lshlrev_b64 v[146:147], 1, v[146:147]
	v_lshl_add_u64 v[154:155], v[154:155], 0, v[146:147]
	v_mul_f32_e32 v124, 0x3dd53b94, v124
	v_mul_f32_e32 v125, 0x3dd53b94, v125
	v_cvt_pk_bf16_f32 v124, v124, v125
	v_mul_f32_e32 v126, 0x3dd53b94, v126
	v_mul_f32_e32 v127, 0x3dd53b94, v127
	v_cvt_pk_bf16_f32 v125, v126, v127
	v_mul_f32_e32 v120, 0x3dd53b94, v120
	v_mul_f32_e32 v121, 0x3dd53b94, v121
	v_cvt_pk_bf16_f32 v126, v120, v121
	v_mul_f32_e32 v122, 0x3dd53b94, v122
	v_mul_f32_e32 v123, 0x3dd53b94, v123
	v_cvt_pk_bf16_f32 v127, v122, v123
	global_store_dwordx4 v[154:155], v[124:127], off nt
	v_mul_f32_e32 v112, 0x3dd53b94, v112
	v_mul_f32_e32 v113, 0x3dd53b94, v113
	v_cvt_pk_bf16_f32 v112, v112, v113
	v_mul_f32_e32 v114, 0x3dd53b94, v114
	v_mul_f32_e32 v115, 0x3dd53b94, v115
	v_cvt_pk_bf16_f32 v113, v114, v115
	v_mul_f32_e32 v104, 0x3dd53b94, v104
	v_mul_f32_e32 v105, 0x3dd53b94, v105
	v_cvt_pk_bf16_f32 v114, v104, v105
	v_or_b32_e32 v104, 16, v156
	v_mad_i64_i32 v[104:105], s[16:17], v104, s62, v[144:145]
	v_mul_f32_e32 v106, 0x3dd53b94, v106
	v_mul_f32_e32 v107, 0x3dd53b94, v107
	v_cvt_pk_bf16_f32 v115, v106, v107
	global_store_dwordx4 v[154:155], v[112:115], off offset:256 nt
	s_and_b64 vcc, exec, s[0:1]
	s_mov_b64 s[0:1], -1
	v_lshl_add_u64 v[112:113], v[104:105], 0, v[146:147]
	v_mul_f32_e32 v116, 0x3dd53b94, v116
	v_mul_f32_e32 v117, 0x3dd53b94, v117
	v_cvt_pk_bf16_f32 v104, v116, v117
	v_mul_f32_e32 v118, 0x3dd53b94, v118
	v_mul_f32_e32 v119, 0x3dd53b94, v119
	v_cvt_pk_bf16_f32 v105, v118, v119
	v_mul_f32_e32 v108, 0x3dd53b94, v108
	v_mul_f32_e32 v109, 0x3dd53b94, v109
	v_cvt_pk_bf16_f32 v106, v108, v109
	v_mul_f32_e32 v110, 0x3dd53b94, v110
	v_mul_f32_e32 v111, 0x3dd53b94, v111
	v_cvt_pk_bf16_f32 v107, v110, v111
	global_store_dwordx4 v[112:113], v[104:107], off nt
	v_mul_f32_e32 v96, 0x3dd53b94, v96
	v_mul_f32_e32 v97, 0x3dd53b94, v97
	v_cvt_pk_bf16_f32 v96, v96, v97
	v_mul_f32_e32 v98, 0x3dd53b94, v98
	v_mul_f32_e32 v99, 0x3dd53b94, v99
	v_cvt_pk_bf16_f32 v97, v98, v99
	v_mul_f32_e32 v88, 0x3dd53b94, v88
	v_mul_f32_e32 v89, 0x3dd53b94, v89
	v_cvt_pk_bf16_f32 v98, v88, v89
	v_or_b32_e32 v88, 32, v156
	v_mad_i64_i32 v[88:89], s[16:17], v88, s62, v[144:145]
	v_mul_f32_e32 v90, 0x3dd53b94, v90
	v_mul_f32_e32 v91, 0x3dd53b94, v91
	v_cvt_pk_bf16_f32 v99, v90, v91
	global_store_dwordx4 v[112:113], v[96:99], off offset:256 nt
	s_nop 1
	v_lshl_add_u64 v[96:97], v[88:89], 0, v[146:147]
	v_mul_f32_e32 v100, 0x3dd53b94, v100
	v_mul_f32_e32 v101, 0x3dd53b94, v101
	v_cvt_pk_bf16_f32 v88, v100, v101
	v_mul_f32_e32 v102, 0x3dd53b94, v102
	v_mul_f32_e32 v103, 0x3dd53b94, v103
	v_cvt_pk_bf16_f32 v89, v102, v103
	v_mul_f32_e32 v92, 0x3dd53b94, v92
	v_mul_f32_e32 v93, 0x3dd53b94, v93
	v_cvt_pk_bf16_f32 v90, v92, v93
	v_mul_f32_e32 v94, 0x3dd53b94, v94
	v_mul_f32_e32 v95, 0x3dd53b94, v95
	v_cvt_pk_bf16_f32 v91, v94, v95
	global_store_dwordx4 v[96:97], v[88:91], off nt
	v_mul_f32_e32 v80, 0x3dd53b94, v80
	v_mul_f32_e32 v81, 0x3dd53b94, v81
	v_cvt_pk_bf16_f32 v80, v80, v81
	v_mul_f32_e32 v82, 0x3dd53b94, v82
	v_mul_f32_e32 v83, 0x3dd53b94, v83
	v_cvt_pk_bf16_f32 v81, v82, v83
	v_mul_f32_e32 v72, 0x3dd53b94, v72
	v_mul_f32_e32 v73, 0x3dd53b94, v73
	v_cvt_pk_bf16_f32 v82, v72, v73
	v_or_b32_e32 v72, 48, v156
	v_mad_i64_i32 v[72:73], s[16:17], v72, s62, v[144:145]
	v_mul_f32_e32 v74, 0x3dd53b94, v74
	v_mul_f32_e32 v75, 0x3dd53b94, v75
	v_cvt_pk_bf16_f32 v83, v74, v75
	global_store_dwordx4 v[96:97], v[80:83], off offset:256 nt
	s_nop 1
	v_lshl_add_u64 v[80:81], v[72:73], 0, v[146:147]
	v_mul_f32_e32 v84, 0x3dd53b94, v84
	v_mul_f32_e32 v85, 0x3dd53b94, v85
	v_cvt_pk_bf16_f32 v72, v84, v85
	v_mul_f32_e32 v86, 0x3dd53b94, v86
	v_mul_f32_e32 v87, 0x3dd53b94, v87
	v_cvt_pk_bf16_f32 v73, v86, v87
	v_mul_f32_e32 v76, 0x3dd53b94, v76
	v_mul_f32_e32 v77, 0x3dd53b94, v77
	v_cvt_pk_bf16_f32 v74, v76, v77
	v_mul_f32_e32 v78, 0x3dd53b94, v78
	v_mul_f32_e32 v79, 0x3dd53b94, v79
	v_cvt_pk_bf16_f32 v75, v78, v79
	global_store_dwordx4 v[80:81], v[72:75], off nt
	v_mul_f32_e32 v68, 0x3dd53b94, v68
	v_mul_f32_e32 v69, 0x3dd53b94, v69
	v_cvt_pk_bf16_f32 v68, v68, v69
	v_mul_f32_e32 v70, 0x3dd53b94, v70
	v_mul_f32_e32 v71, 0x3dd53b94, v71
	v_cvt_pk_bf16_f32 v69, v70, v71
	v_mul_f32_e32 v64, 0x3dd53b94, v64
	v_mul_f32_e32 v65, 0x3dd53b94, v65
	v_cvt_pk_bf16_f32 v70, v64, v65
	v_add_u32_e32 v64, 0x80, v156
	v_mad_i64_i32 v[64:65], s[16:17], v64, s62, v[144:145]
	v_lshl_add_u64 v[64:65], v[64:65], 0, v[146:147]
	v_mul_f32_e32 v66, 0x3dd53b94, v66
	v_mul_f32_e32 v67, 0x3dd53b94, v67
	v_cvt_pk_bf16_f32 v71, v66, v67
	global_store_dwordx4 v[80:81], v[68:71], off offset:256 nt
	v_mul_f32_e32 v60, 0x3dd53b94, v60
	v_mul_f32_e32 v61, 0x3dd53b94, v61
	v_cvt_pk_bf16_f32 v60, v60, v61
	v_mul_f32_e32 v62, 0x3dd53b94, v62
	v_mul_f32_e32 v63, 0x3dd53b94, v63
	v_cvt_pk_bf16_f32 v61, v62, v63
	v_mul_f32_e32 v56, 0x3dd53b94, v56
	v_mul_f32_e32 v57, 0x3dd53b94, v57
	v_cvt_pk_bf16_f32 v62, v56, v57
	v_mul_f32_e32 v58, 0x3dd53b94, v58
	v_mul_f32_e32 v59, 0x3dd53b94, v59
	v_cvt_pk_bf16_f32 v63, v58, v59
	global_store_dwordx4 v[64:65], v[60:63], off nt
	v_mul_f32_e32 v48, 0x3dd53b94, v48
	v_mul_f32_e32 v49, 0x3dd53b94, v49
	v_cvt_pk_bf16_f32 v48, v48, v49
	v_mul_f32_e32 v50, 0x3dd53b94, v50
	v_mul_f32_e32 v51, 0x3dd53b94, v51
	v_cvt_pk_bf16_f32 v49, v50, v51
	v_mul_f32_e32 v40, 0x3dd53b94, v40
	v_mul_f32_e32 v41, 0x3dd53b94, v41
	v_cvt_pk_bf16_f32 v50, v40, v41
	v_add_u32_e32 v40, 0x90, v156
	v_mad_i64_i32 v[40:41], s[16:17], v40, s62, v[144:145]
	v_mul_f32_e32 v42, 0x3dd53b94, v42
	v_mul_f32_e32 v43, 0x3dd53b94, v43
	v_cvt_pk_bf16_f32 v51, v42, v43
	global_store_dwordx4 v[64:65], v[48:51], off offset:256 nt
	s_nop 1
	v_lshl_add_u64 v[48:49], v[40:41], 0, v[146:147]
	v_mul_f32_e32 v52, 0x3dd53b94, v52
	v_mul_f32_e32 v53, 0x3dd53b94, v53
	v_cvt_pk_bf16_f32 v40, v52, v53
	v_mul_f32_e32 v54, 0x3dd53b94, v54
	v_mul_f32_e32 v55, 0x3dd53b94, v55
	v_cvt_pk_bf16_f32 v41, v54, v55
	v_mul_f32_e32 v44, 0x3dd53b94, v44
	v_mul_f32_e32 v45, 0x3dd53b94, v45
	v_cvt_pk_bf16_f32 v42, v44, v45
	v_mul_f32_e32 v46, 0x3dd53b94, v46
	v_mul_f32_e32 v47, 0x3dd53b94, v47
	v_cvt_pk_bf16_f32 v43, v46, v47
	global_store_dwordx4 v[48:49], v[40:43], off nt
	v_mul_f32_e32 v32, 0x3dd53b94, v32
	v_mul_f32_e32 v33, 0x3dd53b94, v33
	v_cvt_pk_bf16_f32 v32, v32, v33
	v_mul_f32_e32 v34, 0x3dd53b94, v34
	v_mul_f32_e32 v35, 0x3dd53b94, v35
	v_cvt_pk_bf16_f32 v33, v34, v35
	v_mul_f32_e32 v24, 0x3dd53b94, v24
	v_mul_f32_e32 v25, 0x3dd53b94, v25
	v_cvt_pk_bf16_f32 v34, v24, v25
	v_add_u32_e32 v24, 0xa0, v156
	v_mad_i64_i32 v[24:25], s[16:17], v24, s62, v[144:145]
	v_mul_f32_e32 v26, 0x3dd53b94, v26
	v_mul_f32_e32 v27, 0x3dd53b94, v27
	v_cvt_pk_bf16_f32 v35, v26, v27
	global_store_dwordx4 v[48:49], v[32:35], off offset:256 nt
	s_nop 1
	v_lshl_add_u64 v[32:33], v[24:25], 0, v[146:147]
	v_mul_f32_e32 v36, 0x3dd53b94, v36
	v_mul_f32_e32 v37, 0x3dd53b94, v37
	v_cvt_pk_bf16_f32 v24, v36, v37
	v_mul_f32_e32 v38, 0x3dd53b94, v38
	v_mul_f32_e32 v39, 0x3dd53b94, v39
	v_cvt_pk_bf16_f32 v25, v38, v39
	v_mul_f32_e32 v28, 0x3dd53b94, v28
	v_mul_f32_e32 v29, 0x3dd53b94, v29
	v_cvt_pk_bf16_f32 v26, v28, v29
	v_mul_f32_e32 v30, 0x3dd53b94, v30
	v_mul_f32_e32 v31, 0x3dd53b94, v31
	v_cvt_pk_bf16_f32 v27, v30, v31
	global_store_dwordx4 v[32:33], v[24:27], off nt
	v_mul_f32_e32 v16, 0x3dd53b94, v16
	v_mul_f32_e32 v17, 0x3dd53b94, v17
	v_cvt_pk_bf16_f32 v16, v16, v17
	v_mul_f32_e32 v18, 0x3dd53b94, v18
	v_mul_f32_e32 v19, 0x3dd53b94, v19
	v_cvt_pk_bf16_f32 v17, v18, v19
	v_mul_f32_e32 v8, 0x3dd53b94, v8
	v_mul_f32_e32 v9, 0x3dd53b94, v9
	v_cvt_pk_bf16_f32 v18, v8, v9
	v_add_u32_e32 v8, 0xb0, v156
	v_mad_i64_i32 v[8:9], s[16:17], v8, s62, v[144:145]
	v_mul_f32_e32 v10, 0x3dd53b94, v10
	v_mul_f32_e32 v11, 0x3dd53b94, v11
	v_cvt_pk_bf16_f32 v19, v10, v11
	global_store_dwordx4 v[32:33], v[16:19], off offset:256 nt
	s_nop 1
	v_lshl_add_u64 v[16:17], v[8:9], 0, v[146:147]
	v_mul_f32_e32 v20, 0x3dd53b94, v20
	v_mul_f32_e32 v21, 0x3dd53b94, v21
	v_cvt_pk_bf16_f32 v8, v20, v21
	v_mul_f32_e32 v22, 0x3dd53b94, v22
	v_mul_f32_e32 v23, 0x3dd53b94, v23
	v_cvt_pk_bf16_f32 v9, v22, v23
	v_mul_f32_e32 v12, 0x3dd53b94, v12
	v_mul_f32_e32 v13, 0x3dd53b94, v13
	v_cvt_pk_bf16_f32 v10, v12, v13
	v_mul_f32_e32 v14, 0x3dd53b94, v14
	v_mul_f32_e32 v15, 0x3dd53b94, v15
	v_cvt_pk_bf16_f32 v11, v14, v15
	global_store_dwordx4 v[16:17], v[8:11], off nt
	v_mul_f32_e32 v4, 0x3dd53b94, v4
	v_mul_f32_e32 v5, 0x3dd53b94, v5
	v_cvt_pk_bf16_f32 v4, v4, v5
	v_mul_f32_e32 v6, 0x3dd53b94, v6
	v_mul_f32_e32 v7, 0x3dd53b94, v7
	v_cvt_pk_bf16_f32 v5, v6, v7
	v_mul_f32_e32 v0, 0x3dd53b94, v0
	v_mul_f32_e32 v1, 0x3dd53b94, v1
	v_cvt_pk_bf16_f32 v6, v0, v1
	v_mul_f32_e32 v2, 0x3dd53b94, v2
	v_mul_f32_e32 v3, 0x3dd53b94, v3
	v_cvt_pk_bf16_f32 v7, v2, v3
	global_store_dwordx4 v[16:17], v[4:7], off offset:256 nt
	s_cbranch_vccnz .LBB0_1258
	s_andn2_b64 vcc, exec, s[8:9]
	s_cbranch_vccnz .LBB0_1257
	s_barrier
	s_branch .LBB0_1257
